# v94 + sqticket: down-skinny tile queue fetches its next ticket one tile ahead (atomic round trip overlaps the tile K loop)
# baseline (speedup 1.0000x reference)
.LBB0_1868:
	s_or_b64 exec, exec, s[2:3]
	v_readlane_b32 s2, v255, 53
	v_readlane_b32 s3, v255, 54
	s_lshl_b64 s[2:3], s[2:3], 2
	s_waitcnt lgkmcnt(0)
	s_add_u32 s6, s26, s2
	s_addc_u32 s7, s27, s3
	s_add_u32 s10, s6, 0x8400
	s_addc_u32 s11, s7, 0
	s_add_u32 s14, s26, 0x1de00000
	s_addc_u32 s15, s27, 0
	s_lshl_b64 s[6:7], s[12:13], 3
	v_and_b32_e32 v29, 15, v190
	v_bfe_u32 v3, v190, 4, 2
	s_add_u32 s6, s26, s6
	v_lshlrev_b32_e32 v2, 3, v3
	v_lshlrev_b32_e32 v3, 4, v3
	v_lshlrev_b32_e32 v4, 7, v29
	v_lshlrev_b32_e32 v28, 2, v190
	s_addc_u32 s7, s27, s7
	v_add3_u32 v30, 0, v3, v4
	v_ashrrev_i32_e32 v3, 3, v190
	v_and_b32_e32 v31, 28, v28
	s_add_u32 s18, s6, 0x31000
	s_movk_i32 s6, 0x100
	v_lshlrev_b32_e32 v4, 7, v3
	v_lshlrev_b32_e32 v5, 2, v31
	s_addc_u32 s19, s7, 0
	v_cmp_gt_i32_e64 s[38:39], s6, v190
	v_add3_u32 v32, 0, v4, v5
	v_add_u32_e32 v33, 0x2000, v3
	v_lshlrev_b32_e32 v18, 1, v2
	s_waitcnt vmcnt(0)
	s_barrier
	s_and_saveexec_b64 s[100:101], s[36:37]
	s_cbranch_execz .Lmy_tk_first
	v_mov_b32_e32 v112, 1
	global_atomic_add v112, v181, v112, s[10:11] sc0
.Lmy_tk_first:
	s_mov_b64 exec, s[100:101]
	s_branch .LBB0_1871

.LBB0_1871:
	s_and_saveexec_b64 s[22:23], s[36:37]
	s_cbranch_execz .LBB0_1875
	s_mov_b64 s[28:29], exec
	v_mbcnt_lo_u32_b32 v2, s28, 0
	v_mbcnt_hi_u32_b32 v2, s29, v2
	v_cmp_eq_u32_e32 vcc, 0, v2
	s_and_saveexec_b64 s[26:27], vcc
	s_cbranch_execz .LBB0_1874
	s_waitcnt vmcnt(0)
	v_mov_b32_e32 v3, v112
	v_mov_b32_e32 v112, 1
	global_atomic_add v112, v181, v112, s[10:11] sc0
.LBB0_1874:
	s_or_b64 exec, exec, s[26:27]
	v_readfirstlane_b32 s6, v3
	s_nop 1
	v_add_u32_e32 v2, s6, v2
	v_readlane_b32 s6, v255, 35
	s_nop 1
	v_mov_b32_e32 v3, s6
	ds_write_b32 v3, v2
